# sample-row mini GEMMs: K loop unrolled with 3-4 steps of fragment loads in flight (was one round trip per step)
# speedup vs baseline: 1.0024x; 1.0024x over previous
; DI unsigned pk2(float a, float b) { f32x2 v = {a, b}; bfv2 r = __builtin_convertvector(v, bfv2); return __builtin_bit_cast(unsigned, r); }
; template <bool A_F32>
; DI void mini_gemm(f32x4 (&acc)[2][2], const void* Ap, int lda, const bf16_t* Bp, int ldb, int K, int wave, int l15, int quad) {
;   const int kw = K >> 2, k0 = wave * kw;
; #pragma unroll 2
;   for (int ks = 0; ks < kw; ks += 32) {
;     bf16x8 a[2], b[2];
; #pragma unroll
;     for (int mi = 0; mi < 2; ++mi) {
;       if (A_F32) {
;         const float* ap = (const float*)Ap + (size_t)(mi * 16 + l15) * lda + k0 + ks + quad * 8;
;         const f32x4 v0 = *(const f32x4*)ap, v1 = *(const f32x4*)(ap + 4);
;         u32x4 t; t[0] = pk2(v0[0], v0[1]); t[1] = pk2(v0[2], v0[3]); t[2] = pk2(v1[0], v1[1]); t[3] = pk2(v1[2], v1[3]);
;         a[mi] = __builtin_bit_cast(bf16x8, t);
;       } else {
;         a[mi] = *(const bf16x8*)((const bf16_t*)Ap + (size_t)(mi * 16 + l15) * lda + k0 + ks + quad * 8);
;       }
;       b[mi] = *(const bf16x8*)(Bp + (size_t)(mi * 16 + l15) * ldb + k0 + ks + quad * 8);
;     }
; #pragma unroll
;     for (int mi = 0; mi < 2; ++mi)
; #pragma unroll
;       for (int ni = 0; ni < 2; ++ni) acc[mi][ni] = __builtin_amdgcn_mfma_f32_16x16x32_bf16(b[ni], a[mi], acc[mi][ni], 0, 0, 0);
;   }
; }
; DI f32x4 mini_reduce(const f32x4 (&acc)[2][2], char* lds, int wave, int lane) {
;   float* red = (float*)lds;
;   __syncthreads();
; #pragma unroll
;   for (int i = 0; i < 2; ++i)
; #pragma unroll
;     for (int j = 0; j < 2; ++j)
; #pragma unroll
;       for (int e = 0; e < 4; ++e) red[((wave * 4 + i * 2 + j) * 4 + e) * 64 + lane] = acc[i][j][e];
;   __syncthreads();
;   f32x4 r;
; #pragma unroll
;   for (int e = 0; e < 4; ++e) r[e] = (red[((0 * 4 + wave) * 4 + e) * 64 + lane] + red[((1 * 4 + wave) * 4 + e) * 64 + lane]) + (red[((2 * 4 + wave) * 4 + e) * 64 + lane] + red[((3 * 4 + wave) * 4 + e) * 64 + lane]);
;   return r;
; }
; DI void mini_merge(const Params& p, int l, int t, char* lds) {
;     ...
;   f32x4 acc[2][2]; zero_mini(acc);
;   mini_gemm<false>(acc, p.o_r + (size_t)R0 * 512, 512, p.wt_brr + (size_t)C0 * 512, 512, 512, wave, l15, quad);
;   const f32x4 v1 = mini_reduce(acc, lds, wave, lane);
;   zero_mini(acc);
;   mini_gemm<false>(acc, p.o_a + (size_t)R0 * 512, 512, p.wt_bra + (size_t)C0 * 512, 512, 512, wave, l15, quad);
.LBB0_725:
	v_lshl_add_u64 v[36:37], v[18:19], 0, s[0:1]
	v_lshl_add_u64 v[124:125], v[20:21], 0, s[0:1]
	v_add_co_u32_e32 v80, vcc, s91, v36
	s_nop 1
	v_addc_co_u32_e32 v81, vcc, 0, v37, vcc
	v_add_co_u32_e32 v214, vcc, s91, v124
	s_nop 1
	v_addc_co_u32_e32 v215, vcc, 0, v125, vcc
	global_load_dwordx4 v[22:25], v[36:37], off
	global_load_dwordx4 v[30:33], v[124:125], off
	global_load_dwordx4 v[26:29], v[80:81], off
	global_load_dwordx4 v[40:43], v[214:215], off
	global_load_dwordx4 v[44:47], v[36:37], off offset:64
	global_load_dwordx4 v[52:55], v[124:125], off offset:64
	global_load_dwordx4 v[48:51], v[80:81], off offset:64
	global_load_dwordx4 v[56:59], v[214:215], off offset:64
	global_load_dwordx4 v[60:63], v[36:37], off offset:128
	global_load_dwordx4 v[68:71], v[124:125], off offset:128
	global_load_dwordx4 v[64:67], v[80:81], off offset:128
	global_load_dwordx4 v[72:75], v[214:215], off offset:128
	global_load_dwordx4 v[76:79], v[36:37], off offset:192
	global_load_dwordx4 v[116:119], v[124:125], off offset:192
	global_load_dwordx4 v[112:115], v[80:81], off offset:192
	global_load_dwordx4 v[120:123], v[214:215], off offset:192
	s_waitcnt vmcnt(12)
	v_mfma_f32_16x16x32_bf16 v[14:17], v[30:33], v[22:25], v[14:17]
	v_mfma_f32_16x16x32_bf16 v[10:13], v[40:43], v[22:25], v[10:13]
	v_mfma_f32_16x16x32_bf16 v[6:9], v[30:33], v[26:29], v[6:9]
	v_mfma_f32_16x16x32_bf16 v[2:5], v[40:43], v[26:29], v[2:5]
	s_waitcnt vmcnt(8)
	v_mfma_f32_16x16x32_bf16 v[14:17], v[52:55], v[44:47], v[14:17]
	v_mfma_f32_16x16x32_bf16 v[10:13], v[56:59], v[44:47], v[10:13]
	v_mfma_f32_16x16x32_bf16 v[6:9], v[52:55], v[48:51], v[6:9]
	v_mfma_f32_16x16x32_bf16 v[2:5], v[56:59], v[48:51], v[2:5]
	s_waitcnt vmcnt(4)
	v_mfma_f32_16x16x32_bf16 v[14:17], v[68:71], v[60:63], v[14:17]
	v_mfma_f32_16x16x32_bf16 v[10:13], v[72:75], v[60:63], v[10:13]
	v_mfma_f32_16x16x32_bf16 v[6:9], v[68:71], v[64:67], v[6:9]
	v_mfma_f32_16x16x32_bf16 v[2:5], v[72:75], v[64:67], v[2:5]
	s_waitcnt vmcnt(0)
	v_mfma_f32_16x16x32_bf16 v[14:17], v[116:119], v[76:79], v[14:17]
	v_mfma_f32_16x16x32_bf16 v[10:13], v[120:123], v[76:79], v[10:13]
	v_mfma_f32_16x16x32_bf16 v[6:9], v[116:119], v[112:115], v[6:9]
	v_mfma_f32_16x16x32_bf16 v[2:5], v[120:123], v[112:115], v[2:5]
	v_and_b32_e32 v41, 63, v38
	s_lshl_b32 s23, s20, 10
	v_lshlrev_b32_e32 v40, 2, v41
	s_lshl_b32 s24, s20, 12
	v_or_b32_e32 v18, s24, v40
	v_or_b32_e32 v39, s23, v40
	s_waitcnt lgkmcnt(0)
	s_barrier
	ds_write2st64_b32 v18, v14, v15 offset1:1
	ds_write2st64_b32 v18, v16, v17 offset0:2 offset1:3
	ds_write2st64_b32 v18, v10, v11 offset0:4 offset1:5
	ds_write2st64_b32 v18, v12, v13 offset0:6 offset1:7
	ds_write2st64_b32 v18, v6, v7 offset0:8 offset1:9
	ds_write2st64_b32 v18, v8, v9 offset0:10 offset1:11
	ds_write2st64_b32 v18, v2, v3 offset0:12 offset1:13
	ds_write2st64_b32 v18, v4, v5 offset0:14 offset1:15
	s_waitcnt lgkmcnt(0)
	s_barrier
	ds_read2st64_b32 v[18:19], v39 offset1:1
	ds_read2st64_b32 v[20:21], v39 offset0:16 offset1:17
	ds_read2st64_b32 v[26:27], v39 offset0:18 offset1:19
	ds_read2st64_b32 v[28:29], v39 offset0:2 offset1:3
	ds_read2st64_b32 v[22:23], v39 offset0:32 offset1:33
	ds_read2st64_b32 v[24:25], v39 offset0:48 offset1:49
	ds_read2st64_b32 v[30:31], v39 offset0:50 offset1:51
	ds_read2st64_b32 v[32:33], v39 offset0:34 offset1:35
	v_readlane_b32 s68, v251, 49
	v_readlane_b32 s76, v251, 57
	v_readlane_b32 s77, v251, 58
	v_mov_b32_e32 v2, 0
	v_lshl_add_u64 v[34:35], s[54:55], 0, v[34:35]
	v_lshl_add_u64 v[36:37], s[76:77], 0, v[0:1]
	s_movk_i32 s25, 0xffe0
	v_mov_b32_e32 v3, v2
	v_mov_b32_e32 v4, v2
	v_mov_b32_e32 v5, v2
	v_mov_b32_e32 v6, v2
	v_mov_b32_e32 v7, v2
	v_mov_b32_e32 v8, v2
	v_mov_b32_e32 v9, v2
	v_mov_b32_e32 v10, v2
	v_mov_b32_e32 v11, v2
	v_mov_b32_e32 v12, v2
	v_mov_b32_e32 v13, v2
	v_mov_b32_e32 v14, v2
	v_mov_b32_e32 v15, v2
	v_mov_b32_e32 v16, v2
	v_mov_b32_e32 v17, v2
	v_readlane_b32 s69, v251, 50
	v_readlane_b32 s70, v251, 51
	v_readlane_b32 s71, v251, 52
	v_readlane_b32 s72, v251, 53
	v_readlane_b32 s73, v251, 54
	v_readlane_b32 s74, v251, 55
	v_readlane_b32 s75, v251, 56
	v_readlane_b32 s78, v251, 59
	v_readlane_b32 s79, v251, 60
	v_readlane_b32 s80, v251, 61
	v_readlane_b32 s81, v251, 62
	v_readlane_b32 s82, v251, 63
	v_readlane_b32 s83, v252, 0
; DI unsigned pk2(float a, float b) { f32x2 v = {a, b}; bfv2 r = __builtin_convertvector(v, bfv2); return __builtin_bit_cast(unsigned, r); }
; DI float bf_lo(unsigned u) { return __uint_as_float(u << 16); }
; DI float bf_hi(unsigned u) { return __uint_as_float(u & 0xffff0000u); }
; template <bool A_F32>
; DI void mini_gemm(f32x4 (&acc)[2][2], const void* Ap, int lda, const bf16_t* Bp, int ldb, int K, int wave, int l15, int quad) {
;   const int kw = K >> 2, k0 = wave * kw;
; #pragma unroll 2
;   for (int ks = 0; ks < kw; ks += 32) {
;     bf16x8 a[2], b[2];
; #pragma unroll
;     for (int mi = 0; mi < 2; ++mi) {
;       if (A_F32) {
;         const float* ap = (const float*)Ap + (size_t)(mi * 16 + l15) * lda + k0 + ks + quad * 8;
;         const f32x4 v0 = *(const f32x4*)ap, v1 = *(const f32x4*)(ap + 4);
;         u32x4 t; t[0] = pk2(v0[0], v0[1]); t[1] = pk2(v0[2], v0[3]); t[2] = pk2(v1[0], v1[1]); t[3] = pk2(v1[2], v1[3]);
;         a[mi] = __builtin_bit_cast(bf16x8, t);
;       } else {
;         a[mi] = *(const bf16x8*)((const bf16_t*)Ap + (size_t)(mi * 16 + l15) * lda + k0 + ks + quad * 8);
;       }
;       b[mi] = *(const bf16x8*)(Bp + (size_t)(mi * 16 + l15) * ldb + k0 + ks + quad * 8);
;     }
; #pragma unroll
;     for (int mi = 0; mi < 2; ++mi)
; #pragma unroll
;       for (int ni = 0; ni < 2; ++ni) acc[mi][ni] = __builtin_amdgcn_mfma_f32_16x16x32_bf16(b[ni], a[mi], acc[mi][ni], 0, 0, 0);
;   }
; DI void mini_merge(const Params& p, int l, int t, char* lds) {
;     ...
;   const f32x4 v2 = mini_reduce(acc, lds, wave, lane);
;   const int R = R0 + (wave >> 1) * 16 + l15, c = C0 + (wave & 1) * 16 + quad * 4;
;   const u32x2 g1 = *(const u32x2*)(p.z + (size_t)R * NZ + C_MR + c), g2 = *(const u32x2*)(p.z + (size_t)R * NZ + C_MA + c);
;   u32x2 o;
;   o[0] = pk2(bf_lo(g1[0]) * v1[0] + bf_lo(g2[0]) * v2[0], bf_hi(g1[0]) * v1[1] + bf_hi(g2[0]) * v2[1]);
;   o[1] = pk2(bf_lo(g1[1]) * v1[2] + bf_lo(g2[1]) * v2[2], bf_hi(g1[1]) * v1[3] + bf_hi(g2[1]) * v2[3]);
;   *(u32x2*)(p.hn + (size_t)R * DM + c) = o;
.LBB0_727:
	v_lshl_add_u64 v[34:35], v[34:35], 0, s[0:1]
	v_lshl_add_u64 v[36:37], v[36:37], 0, s[0:1]
	v_add_co_u32_e32 v120, vcc, s91, v34
	s_nop 1
	v_addc_co_u32_e32 v121, vcc, 0, v35, vcc
	v_add_co_u32_e32 v122, vcc, s91, v36
	s_nop 1
	v_addc_co_u32_e32 v123, vcc, 0, v37, vcc
	global_load_dwordx4 v[42:45], v[34:35], off
	global_load_dwordx4 v[50:53], v[36:37], off
	global_load_dwordx4 v[46:49], v[120:121], off
	global_load_dwordx4 v[54:57], v[122:123], off
	global_load_dwordx4 v[58:61], v[34:35], off offset:64
	global_load_dwordx4 v[66:69], v[36:37], off offset:64
	global_load_dwordx4 v[62:65], v[120:121], off offset:64
	global_load_dwordx4 v[70:73], v[122:123], off offset:64
	global_load_dwordx4 v[74:77], v[34:35], off offset:128
	global_load_dwordx4 v[112:115], v[36:37], off offset:128
	global_load_dwordx4 v[78:81], v[120:121], off offset:128
	global_load_dwordx4 v[116:119], v[122:123], off offset:128
	s_waitcnt vmcnt(8)
	v_mfma_f32_16x16x32_bf16 v[14:17], v[50:53], v[42:45], v[14:17]
	v_mfma_f32_16x16x32_bf16 v[10:13], v[54:57], v[42:45], v[10:13]
	v_mfma_f32_16x16x32_bf16 v[6:9], v[50:53], v[46:49], v[6:9]
	v_mfma_f32_16x16x32_bf16 v[2:5], v[54:57], v[46:49], v[2:5]
	global_load_dwordx4 v[42:45], v[34:35], off offset:192
	global_load_dwordx4 v[50:53], v[36:37], off offset:192
	global_load_dwordx4 v[46:49], v[120:121], off offset:192
	global_load_dwordx4 v[54:57], v[122:123], off offset:192
	s_waitcnt vmcnt(8)
	v_mfma_f32_16x16x32_bf16 v[14:17], v[66:69], v[58:61], v[14:17]
	v_mfma_f32_16x16x32_bf16 v[10:13], v[70:73], v[58:61], v[10:13]
	v_mfma_f32_16x16x32_bf16 v[6:9], v[66:69], v[62:65], v[6:9]
	v_mfma_f32_16x16x32_bf16 v[2:5], v[70:73], v[62:65], v[2:5]
	s_waitcnt vmcnt(4)
	v_mfma_f32_16x16x32_bf16 v[14:17], v[112:115], v[74:77], v[14:17]
	v_mfma_f32_16x16x32_bf16 v[10:13], v[116:119], v[74:77], v[10:13]
	v_mfma_f32_16x16x32_bf16 v[6:9], v[112:115], v[78:81], v[6:9]
	v_mfma_f32_16x16x32_bf16 v[2:5], v[116:119], v[78:81], v[2:5]
	s_waitcnt vmcnt(0)
	v_mfma_f32_16x16x32_bf16 v[14:17], v[50:53], v[42:45], v[14:17]
	v_mfma_f32_16x16x32_bf16 v[10:13], v[54:57], v[42:45], v[10:13]
	v_mfma_f32_16x16x32_bf16 v[6:9], v[50:53], v[46:49], v[6:9]
	v_mfma_f32_16x16x32_bf16 v[2:5], v[54:57], v[46:49], v[2:5]
	s_ashr_i32 s0, s22, 3
	s_and_b32 s0, s0, -16
	v_add_u32_e32 v0, s24, v40
	s_add_i32 s0, s21, s0
	s_lshl_b32 s1, s3, 5
	s_waitcnt lgkmcnt(0)
	s_barrier
	ds_write2st64_b32 v0, v14, v15 offset1:1
	ds_write2st64_b32 v0, v16, v17 offset0:2 offset1:3
	ds_write2st64_b32 v0, v10, v11 offset0:4 offset1:5
	ds_write2st64_b32 v0, v12, v13 offset0:6 offset1:7
	ds_write2st64_b32 v0, v6, v7 offset0:8 offset1:9
	ds_write2st64_b32 v0, v8, v9 offset0:10 offset1:11
	ds_write2st64_b32 v0, v2, v3 offset0:12 offset1:13
	ds_write2st64_b32 v0, v4, v5 offset0:14 offset1:15
	v_lshrrev_b32_e32 v0, 2, v41
	s_and_b32 s1, s1, 0x3e0
	s_addk_i32 s0, 0x4000
	v_lshl_or_b32 v0, s20, 4, v0
	v_and_or_b32 v2, v38, 15, s0
	v_and_or_b32 v0, v0, 28, s1
	v_mov_b64_e32 v[4:5], s[10:11]
	v_mad_i64_i32 v[4:5], s[0:1], v2, s94, v[4:5]
	v_lshlrev_b32_e32 v0, 1, v0
	v_lshl_add_u64 v[4:5], v[4:5], 0, v[0:1]
	s_movk_i32 s0, 0x2000
	v_add_co_u32_e32 v4, vcc, s0, v4
	s_waitcnt lgkmcnt(0)
	s_nop 0
	v_addc_co_u32_e32 v5, vcc, 0, v5, vcc
	s_barrier
	global_load_dwordx2 v[6:7], v[4:5], off offset:256
	s_nop 0
	global_load_dwordx2 v[4:5], v[4:5], off offset:2304
	v_pk_add_f32 v[8:9], v[28:29], v[26:27]
	v_pk_add_f32 v[10:11], v[32:33], v[30:31]
	v_pk_add_f32 v[12:13], v[18:19], v[20:21]
	v_pk_add_f32 v[14:15], v[22:23], v[24:25]
	v_add_u32_e32 v3, s23, v40
	ds_read2st64_b32 v[16:17], v39 offset1:1
	ds_read2st64_b32 v[18:19], v39 offset0:2 offset1:3
	ds_read2st64_b32 v[20:21], v3 offset0:16 offset1:17
	ds_read2st64_b32 v[22:23], v3 offset0:32 offset1:33
	ds_read2st64_b32 v[24:25], v3 offset0:34 offset1:35
	ds_read2st64_b32 v[26:27], v3 offset0:18 offset1:19
	ds_read2st64_b32 v[28:29], v3 offset0:48 offset1:49
	ds_read2st64_b32 v[30:31], v3 offset0:50 offset1:51
	v_pk_add_f32 v[12:13], v[12:13], v[14:15]
	v_pk_add_f32 v[8:9], v[8:9], v[10:11]
	s_waitcnt lgkmcnt(5)
	v_pk_add_f32 v[10:11], v[16:17], v[20:21]
	s_waitcnt lgkmcnt(1)
	v_pk_add_f32 v[14:15], v[22:23], v[28:29]
	v_pk_add_f32 v[16:17], v[18:19], v[26:27]
	s_waitcnt lgkmcnt(0)
	v_pk_add_f32 v[18:19], v[24:25], v[30:31]
	v_readlane_b32 s20, v254, 52
	v_ashrrev_i32_e32 v3, 31, v2
	v_pk_add_f32 v[10:11], v[10:11], v[14:15]
	v_pk_add_f32 v[14:15], v[16:17], v[18:19]
	v_readlane_b32 s26, v254, 58
	v_readlane_b32 s0, v254, 34
	v_lshlrev_b64 v[2:3], 11, v[2:3]
	s_add_i32 s3, s3, s26
	s_add_i32 s2, s2, s0
	v_lshl_add_u64 v[2:3], s[8:9], 0, v[2:3]
	v_lshl_add_u64 v[2:3], v[2:3], 0, v[0:1]
	s_cmpk_lt_i32 s3, 0x200
	v_readlane_b32 s21, v254, 53
	v_readlane_b32 s22, v254, 54
	v_readlane_b32 s23, v254, 55
	v_readlane_b32 s24, v254, 56
	v_readlane_b32 s25, v254, 57
	v_readlane_b32 s27, v254, 59
	s_waitcnt vmcnt(1)
	v_lshlrev_b32_e32 v16, 16, v6
	s_waitcnt vmcnt(0)
	v_lshlrev_b32_e32 v18, 16, v4
	v_and_b32_e32 v19, 0xffff0000, v4
	v_lshlrev_b32_e32 v4, 16, v5
	v_and_b32_e32 v5, 0xffff0000, v5
	v_and_b32_e32 v17, 0xffff0000, v6
	v_lshlrev_b32_e32 v6, 16, v7
	v_and_b32_e32 v7, 0xffff0000, v7
	v_pk_mul_f32 v[10:11], v[10:11], v[18:19]
	v_pk_mul_f32 v[4:5], v[14:15], v[4:5]
	v_pk_fma_f32 v[10:11], v[12:13], v[16:17], v[10:11]
	v_pk_fma_f32 v[4:5], v[8:9], v[6:7], v[4:5]
	v_cvt_pk_bf16_f32 v6, v10, v11
	v_cvt_pk_bf16_f32 v7, v4, v5
	global_store_dwordx2 v[2:3], v[6:7], off
	s_cbranch_scc1 .LBB0_724

; DI unsigned pk2(float a, float b) { f32x2 v = {a, b}; bfv2 r = __builtin_convertvector(v, bfv2); return __builtin_bit_cast(unsigned, r); }
; template <bool A_F32>
; DI void mini_gemm(f32x4 (&acc)[2][2], const void* Ap, int lda, const bf16_t* Bp, int ldb, int K, int wave, int l15, int quad) {
;   const int kw = K >> 2, k0 = wave * kw;
; #pragma unroll 2
;   for (int ks = 0; ks < kw; ks += 32) {
;     bf16x8 a[2], b[2];
; #pragma unroll
;     for (int mi = 0; mi < 2; ++mi) {
;       if (A_F32) {
;         const float* ap = (const float*)Ap + (size_t)(mi * 16 + l15) * lda + k0 + ks + quad * 8;
;         const f32x4 v0 = *(const f32x4*)ap, v1 = *(const f32x4*)(ap + 4);
;         u32x4 t; t[0] = pk2(v0[0], v0[1]); t[1] = pk2(v0[2], v0[3]); t[2] = pk2(v1[0], v1[1]); t[3] = pk2(v1[2], v1[3]);
;         a[mi] = __builtin_bit_cast(bf16x8, t);
;       } else {
;         a[mi] = *(const bf16x8*)((const bf16_t*)Ap + (size_t)(mi * 16 + l15) * lda + k0 + ks + quad * 8);
;       }
;       b[mi] = *(const bf16x8*)(Bp + (size_t)(mi * 16 + l15) * ldb + k0 + ks + quad * 8);
;     }
; #pragma unroll
;     for (int mi = 0; mi < 2; ++mi)
; #pragma unroll
;       for (int ni = 0; ni < 2; ++ni) acc[mi][ni] = __builtin_amdgcn_mfma_f32_16x16x32_bf16(b[ni], a[mi], acc[mi][ni], 0, 0, 0);
;   }
; }
; DI f32x4 mini_reduce(const f32x4 (&acc)[2][2], char* lds, int wave, int lane) {
;   float* red = (float*)lds;
;   __syncthreads();
; #pragma unroll
;   for (int i = 0; i < 2; ++i)
; #pragma unroll
;     for (int j = 0; j < 2; ++j)
; #pragma unroll
;       for (int e = 0; e < 4; ++e) red[((wave * 4 + i * 2 + j) * 4 + e) * 64 + lane] = acc[i][j][e];
;   __syncthreads();
;   f32x4 r;
; #pragma unroll
;   for (int e = 0; e < 4; ++e) r[e] = (red[((0 * 4 + wave) * 4 + e) * 64 + lane] + red[((1 * 4 + wave) * 4 + e) * 64 + lane]) + (red[((2 * 4 + wave) * 4 + e) * 64 + lane] + red[((3 * 4 + wave) * 4 + e) * 64 + lane]);
; DI void mini_out(const Params& p, int l, int t, char* lds) {
;     ...
;   mini_gemm<false>(acc, p.hn + (size_t)R0 * DM, DM, p.wt_out + (size_t)C0 * DM, DM, DM, wave, l15, quad);
;   const f32x4 v = mini_reduce(acc, lds, wave, lane);
;   const int R = R0 + (wave >> 1) * 16 + l15, c = C0 + (wave & 1) * 16 + quad * 4;
;   const f32x4 xv = *(const f32x4*)(x_row(p, l, R) + c);
.LBB0_834:
	v_lshl_add_u64 v[120:121], v[18:19], 0, s[24:25]
	v_lshl_add_u64 v[124:125], v[20:21], 0, s[24:25]
	v_add_co_u32_e32 v122, vcc, s33, v120
	s_nop 1
	v_addc_co_u32_e32 v123, vcc, 0, v121, vcc
	v_add_co_u32_e32 v80, vcc, s33, v124
	s_nop 1
	v_addc_co_u32_e32 v81, vcc, 0, v125, vcc
	global_load_dwordx4 v[24:27], v[120:121], off
	global_load_dwordx4 v[32:35], v[124:125], off
	global_load_dwordx4 v[28:31], v[122:123], off
	global_load_dwordx4 v[36:39], v[80:81], off
	global_load_dwordx4 v[40:43], v[120:121], off offset:64
	global_load_dwordx4 v[48:51], v[124:125], off offset:64
	global_load_dwordx4 v[44:47], v[122:123], off offset:64
	global_load_dwordx4 v[52:55], v[80:81], off offset:64
	global_load_dwordx4 v[56:59], v[120:121], off offset:128
	global_load_dwordx4 v[64:67], v[124:125], off offset:128
	global_load_dwordx4 v[60:63], v[122:123], off offset:128
	global_load_dwordx4 v[68:71], v[80:81], off offset:128
	global_load_dwordx4 v[72:75], v[120:121], off offset:192
	global_load_dwordx4 v[112:115], v[124:125], off offset:192
	global_load_dwordx4 v[76:79], v[122:123], off offset:192
	global_load_dwordx4 v[116:119], v[80:81], off offset:192
	s_waitcnt vmcnt(12)
	v_mfma_f32_16x16x32_bf16 v[6:9], v[32:35], v[24:27], v[6:9]
	v_mfma_f32_16x16x32_bf16 v[14:17], v[36:39], v[24:27], v[14:17]
	v_mfma_f32_16x16x32_bf16 v[2:5], v[32:35], v[28:31], v[2:5]
	v_mfma_f32_16x16x32_bf16 v[10:13], v[36:39], v[28:31], v[10:13]
	global_load_dwordx4 v[24:27], v[120:121], off offset:256
	global_load_dwordx4 v[32:35], v[124:125], off offset:256
	global_load_dwordx4 v[28:31], v[122:123], off offset:256
	global_load_dwordx4 v[36:39], v[80:81], off offset:256
	s_waitcnt vmcnt(12)
	v_mfma_f32_16x16x32_bf16 v[6:9], v[48:51], v[40:43], v[6:9]
	v_mfma_f32_16x16x32_bf16 v[14:17], v[52:55], v[40:43], v[14:17]
	v_mfma_f32_16x16x32_bf16 v[2:5], v[48:51], v[44:47], v[2:5]
	v_mfma_f32_16x16x32_bf16 v[10:13], v[52:55], v[44:47], v[10:13]
	global_load_dwordx4 v[40:43], v[120:121], off offset:320
	global_load_dwordx4 v[48:51], v[124:125], off offset:320
	global_load_dwordx4 v[44:47], v[122:123], off offset:320
	global_load_dwordx4 v[52:55], v[80:81], off offset:320
	s_waitcnt vmcnt(12)
	v_mfma_f32_16x16x32_bf16 v[6:9], v[64:67], v[56:59], v[6:9]
	v_mfma_f32_16x16x32_bf16 v[14:17], v[68:71], v[56:59], v[14:17]
	v_mfma_f32_16x16x32_bf16 v[2:5], v[64:67], v[60:63], v[2:5]
	v_mfma_f32_16x16x32_bf16 v[10:13], v[68:71], v[60:63], v[10:13]
	global_load_dwordx4 v[56:59], v[120:121], off offset:384
	global_load_dwordx4 v[64:67], v[124:125], off offset:384
	global_load_dwordx4 v[60:63], v[122:123], off offset:384
	global_load_dwordx4 v[68:71], v[80:81], off offset:384
	s_waitcnt vmcnt(12)
	v_mfma_f32_16x16x32_bf16 v[6:9], v[112:115], v[72:75], v[6:9]
	v_mfma_f32_16x16x32_bf16 v[14:17], v[116:119], v[72:75], v[14:17]
	v_mfma_f32_16x16x32_bf16 v[2:5], v[112:115], v[76:79], v[2:5]
	v_mfma_f32_16x16x32_bf16 v[10:13], v[116:119], v[76:79], v[10:13]
	global_load_dwordx4 v[72:75], v[120:121], off offset:448
	global_load_dwordx4 v[112:115], v[124:125], off offset:448
	global_load_dwordx4 v[76:79], v[122:123], off offset:448
	global_load_dwordx4 v[116:119], v[80:81], off offset:448
	s_waitcnt vmcnt(12)
	v_mfma_f32_16x16x32_bf16 v[6:9], v[32:35], v[24:27], v[6:9]
	v_mfma_f32_16x16x32_bf16 v[14:17], v[36:39], v[24:27], v[14:17]
	v_mfma_f32_16x16x32_bf16 v[2:5], v[32:35], v[28:31], v[2:5]
	v_mfma_f32_16x16x32_bf16 v[10:13], v[36:39], v[28:31], v[10:13]
	s_waitcnt vmcnt(8)
	v_mfma_f32_16x16x32_bf16 v[6:9], v[48:51], v[40:43], v[6:9]
	v_mfma_f32_16x16x32_bf16 v[14:17], v[52:55], v[40:43], v[14:17]
	v_mfma_f32_16x16x32_bf16 v[2:5], v[48:51], v[44:47], v[2:5]
	v_mfma_f32_16x16x32_bf16 v[10:13], v[52:55], v[44:47], v[10:13]
	s_waitcnt vmcnt(4)
	v_mfma_f32_16x16x32_bf16 v[6:9], v[64:67], v[56:59], v[6:9]
	v_mfma_f32_16x16x32_bf16 v[14:17], v[68:71], v[56:59], v[14:17]
	v_mfma_f32_16x16x32_bf16 v[2:5], v[64:67], v[60:63], v[2:5]
	v_mfma_f32_16x16x32_bf16 v[10:13], v[68:71], v[60:63], v[10:13]
	s_waitcnt vmcnt(0)
	v_mfma_f32_16x16x32_bf16 v[6:9], v[112:115], v[72:75], v[6:9]
	v_mfma_f32_16x16x32_bf16 v[14:17], v[116:119], v[72:75], v[14:17]
	v_mfma_f32_16x16x32_bf16 v[2:5], v[112:115], v[76:79], v[2:5]
	v_mfma_f32_16x16x32_bf16 v[10:13], v[116:119], v[76:79], v[10:13]
	v_and_b32_e32 v24, 63, v22
	v_lshlrev_b32_e32 v0, 2, v24
	v_lshl_or_b32 v18, s26, 12, v0
	v_lshl_or_b32 v0, s26, 10, v0
	s_barrier
	ds_write2st64_b32 v18, v6, v7 offset1:1
	ds_write2st64_b32 v18, v8, v9 offset0:2 offset1:3
	ds_write2st64_b32 v18, v14, v15 offset0:4 offset1:5
	ds_write2st64_b32 v18, v16, v17 offset0:6 offset1:7
	ds_write2st64_b32 v18, v2, v3 offset0:8 offset1:9
	ds_write2st64_b32 v18, v4, v5 offset0:10 offset1:11
	ds_write2st64_b32 v18, v10, v11 offset0:12 offset1:13
	ds_write2st64_b32 v18, v12, v13 offset0:14 offset1:15
	s_waitcnt lgkmcnt(0)
	s_barrier
	ds_read2st64_b32 v[4:5], v0 offset1:1
	ds_read2st64_b32 v[6:7], v0 offset0:16 offset1:17
	ds_read2st64_b32 v[8:9], v0 offset0:18 offset1:19
	ds_read2st64_b32 v[10:11], v0 offset0:2 offset1:3
	ds_read2st64_b32 v[12:13], v0 offset0:32 offset1:33
	ds_read2st64_b32 v[14:15], v0 offset0:48 offset1:49
	ds_read2st64_b32 v[16:17], v0 offset0:50 offset1:51
	ds_read2st64_b32 v[18:19], v0 offset0:34 offset1:35
	s_ashr_i32 s0, s31, 3
	s_and_b32 s0, s0, -16
	s_add_i32 s0, s27, s0
	s_addk_i32 s0, 0x4000
	v_and_or_b32 v2, v22, 15, s0
	s_and_b64 vcc, exec, s[2:3]
	s_cbranch_vccz .LBB0_837
	v_ashrrev_i32_e32 v3, 31, v2
	s_mov_b64 s[0:1], 0
	s_branch .LBB0_838

; DI unsigned pk2(float a, float b) { f32x2 v = {a, b}; bfv2 r = __builtin_convertvector(v, bfv2); return __builtin_bit_cast(unsigned, r); }
; template <bool A_F32>
; DI void mini_gemm(f32x4 (&acc)[2][2], const void* Ap, int lda, const bf16_t* Bp, int ldb, int K, int wave, int l15, int quad) {
;   const int kw = K >> 2, k0 = wave * kw;
; #pragma unroll 2
;   for (int ks = 0; ks < kw; ks += 32) {
;     bf16x8 a[2], b[2];
; #pragma unroll
;     for (int mi = 0; mi < 2; ++mi) {
;       if (A_F32) {
;         const float* ap = (const float*)Ap + (size_t)(mi * 16 + l15) * lda + k0 + ks + quad * 8;
;         const f32x4 v0 = *(const f32x4*)ap, v1 = *(const f32x4*)(ap + 4);
;         u32x4 t; t[0] = pk2(v0[0], v0[1]); t[1] = pk2(v0[2], v0[3]); t[2] = pk2(v1[0], v1[1]); t[3] = pk2(v1[2], v1[3]);
;         a[mi] = __builtin_bit_cast(bf16x8, t);
;       } else {
;         a[mi] = *(const bf16x8*)((const bf16_t*)Ap + (size_t)(mi * 16 + l15) * lda + k0 + ks + quad * 8);
;       }
;       b[mi] = *(const bf16x8*)(Bp + (size_t)(mi * 16 + l15) * ldb + k0 + ks + quad * 8);
;     }
; #pragma unroll
;     for (int mi = 0; mi < 2; ++mi)
; #pragma unroll
;       for (int ni = 0; ni < 2; ++ni) acc[mi][ni] = __builtin_amdgcn_mfma_f32_16x16x32_bf16(b[ni], a[mi], acc[mi][ni], 0, 0, 0);
;   }
; }
; DI f32x4 mini_reduce(const f32x4 (&acc)[2][2], char* lds, int wave, int lane) {
;   float* red = (float*)lds;
;   __syncthreads();
; #pragma unroll
;   for (int i = 0; i < 2; ++i)
; #pragma unroll
;     for (int j = 0; j < 2; ++j)
; #pragma unroll
;       for (int e = 0; e < 4; ++e) red[((wave * 4 + i * 2 + j) * 4 + e) * 64 + lane] = acc[i][j][e];
;   __syncthreads();
; DI void mini_ple(const Params& p, int l, int t, char* lds) {
;     ...
;   mini_gemm<false>(acc, p.o_r + (size_t)R0 * DM, DM, p.wt_gate + (size_t)C0 * DM, DM, DM, wave, l15, quad);
;   const f32x4 g = mini_reduce(acc, lds, wave, lane);
.LBB0_956:
	v_lshl_add_u64 v[120:121], v[22:23], 0, s[26:27]
	v_lshl_add_u64 v[124:125], v[20:21], 0, s[26:27]
	v_add_co_u32_e32 v122, vcc, s33, v120
	s_nop 1
	v_addc_co_u32_e32 v123, vcc, 0, v121, vcc
	v_add_co_u32_e32 v80, vcc, s33, v124
	s_nop 1
	v_addc_co_u32_e32 v81, vcc, 0, v125, vcc
	global_load_dwordx4 v[24:27], v[120:121], off
	global_load_dwordx4 v[32:35], v[124:125], off
	global_load_dwordx4 v[28:31], v[122:123], off
	global_load_dwordx4 v[36:39], v[80:81], off
	global_load_dwordx4 v[40:43], v[120:121], off offset:64
	global_load_dwordx4 v[48:51], v[124:125], off offset:64
	global_load_dwordx4 v[44:47], v[122:123], off offset:64
	global_load_dwordx4 v[52:55], v[80:81], off offset:64
	global_load_dwordx4 v[56:59], v[120:121], off offset:128
	global_load_dwordx4 v[64:67], v[124:125], off offset:128
	global_load_dwordx4 v[60:63], v[122:123], off offset:128
	global_load_dwordx4 v[68:71], v[80:81], off offset:128
	global_load_dwordx4 v[72:75], v[120:121], off offset:192
	global_load_dwordx4 v[112:115], v[124:125], off offset:192
	global_load_dwordx4 v[76:79], v[122:123], off offset:192
	global_load_dwordx4 v[116:119], v[80:81], off offset:192
	s_waitcnt vmcnt(12)
	v_mfma_f32_16x16x32_bf16 v[6:9], v[32:35], v[24:27], v[6:9]
	v_mfma_f32_16x16x32_bf16 v[14:17], v[36:39], v[24:27], v[14:17]
	v_mfma_f32_16x16x32_bf16 v[2:5], v[32:35], v[28:31], v[2:5]
	v_mfma_f32_16x16x32_bf16 v[10:13], v[36:39], v[28:31], v[10:13]
	global_load_dwordx4 v[24:27], v[120:121], off offset:256
	global_load_dwordx4 v[32:35], v[124:125], off offset:256
	global_load_dwordx4 v[28:31], v[122:123], off offset:256
	global_load_dwordx4 v[36:39], v[80:81], off offset:256
	s_waitcnt vmcnt(12)
	v_mfma_f32_16x16x32_bf16 v[6:9], v[48:51], v[40:43], v[6:9]
	v_mfma_f32_16x16x32_bf16 v[14:17], v[52:55], v[40:43], v[14:17]
	v_mfma_f32_16x16x32_bf16 v[2:5], v[48:51], v[44:47], v[2:5]
	v_mfma_f32_16x16x32_bf16 v[10:13], v[52:55], v[44:47], v[10:13]
	global_load_dwordx4 v[40:43], v[120:121], off offset:320
	global_load_dwordx4 v[48:51], v[124:125], off offset:320
	global_load_dwordx4 v[44:47], v[122:123], off offset:320
	global_load_dwordx4 v[52:55], v[80:81], off offset:320
	s_waitcnt vmcnt(12)
	v_mfma_f32_16x16x32_bf16 v[6:9], v[64:67], v[56:59], v[6:9]
	v_mfma_f32_16x16x32_bf16 v[14:17], v[68:71], v[56:59], v[14:17]
	v_mfma_f32_16x16x32_bf16 v[2:5], v[64:67], v[60:63], v[2:5]
	v_mfma_f32_16x16x32_bf16 v[10:13], v[68:71], v[60:63], v[10:13]
	global_load_dwordx4 v[56:59], v[120:121], off offset:384
	global_load_dwordx4 v[64:67], v[124:125], off offset:384
	global_load_dwordx4 v[60:63], v[122:123], off offset:384
	global_load_dwordx4 v[68:71], v[80:81], off offset:384
	s_waitcnt vmcnt(12)
	v_mfma_f32_16x16x32_bf16 v[6:9], v[112:115], v[72:75], v[6:9]
	v_mfma_f32_16x16x32_bf16 v[14:17], v[116:119], v[72:75], v[14:17]
	v_mfma_f32_16x16x32_bf16 v[2:5], v[112:115], v[76:79], v[2:5]
	v_mfma_f32_16x16x32_bf16 v[10:13], v[116:119], v[76:79], v[10:13]
	global_load_dwordx4 v[72:75], v[120:121], off offset:448
	global_load_dwordx4 v[112:115], v[124:125], off offset:448
	global_load_dwordx4 v[76:79], v[122:123], off offset:448
	global_load_dwordx4 v[116:119], v[80:81], off offset:448
	s_waitcnt vmcnt(12)
	v_mfma_f32_16x16x32_bf16 v[6:9], v[32:35], v[24:27], v[6:9]
	v_mfma_f32_16x16x32_bf16 v[14:17], v[36:39], v[24:27], v[14:17]
	v_mfma_f32_16x16x32_bf16 v[2:5], v[32:35], v[28:31], v[2:5]
	v_mfma_f32_16x16x32_bf16 v[10:13], v[36:39], v[28:31], v[10:13]
	s_waitcnt vmcnt(8)
	v_mfma_f32_16x16x32_bf16 v[6:9], v[48:51], v[40:43], v[6:9]
	v_mfma_f32_16x16x32_bf16 v[14:17], v[52:55], v[40:43], v[14:17]
	v_mfma_f32_16x16x32_bf16 v[2:5], v[48:51], v[44:47], v[2:5]
	v_mfma_f32_16x16x32_bf16 v[10:13], v[52:55], v[44:47], v[10:13]
	s_waitcnt vmcnt(4)
	v_mfma_f32_16x16x32_bf16 v[6:9], v[64:67], v[56:59], v[6:9]
	v_mfma_f32_16x16x32_bf16 v[14:17], v[68:71], v[56:59], v[14:17]
	v_mfma_f32_16x16x32_bf16 v[2:5], v[64:67], v[60:63], v[2:5]
	v_mfma_f32_16x16x32_bf16 v[10:13], v[68:71], v[60:63], v[10:13]
	s_waitcnt vmcnt(0)
	v_mfma_f32_16x16x32_bf16 v[6:9], v[112:115], v[72:75], v[6:9]
	v_mfma_f32_16x16x32_bf16 v[14:17], v[116:119], v[72:75], v[14:17]
	v_mfma_f32_16x16x32_bf16 v[2:5], v[112:115], v[76:79], v[2:5]
	v_mfma_f32_16x16x32_bf16 v[10:13], v[116:119], v[76:79], v[10:13]
	v_and_b32_e32 v20, 63, v19
	v_lshlrev_b32_e32 v0, 2, v20
	v_lshl_or_b32 v44, s36, 12, v0
	v_lshl_or_b32 v45, s36, 10, v0
	s_ashr_i32 s0, s37, 3
	s_barrier
	ds_write2st64_b32 v44, v6, v7 offset1:1
	ds_write2st64_b32 v44, v8, v9 offset0:2 offset1:3
	ds_write2st64_b32 v44, v14, v15 offset0:4 offset1:5
	ds_write2st64_b32 v44, v16, v17 offset0:6 offset1:7
	ds_write2st64_b32 v44, v2, v3 offset0:8 offset1:9
	ds_write2st64_b32 v44, v4, v5 offset0:10 offset1:11
	ds_write2st64_b32 v44, v10, v11 offset0:12 offset1:13
	ds_write2st64_b32 v44, v12, v13 offset0:14 offset1:15
	s_waitcnt lgkmcnt(0)
	s_barrier
; DI unsigned pk2(float a, float b) { f32x2 v = {a, b}; bfv2 r = __builtin_convertvector(v, bfv2); return __builtin_bit_cast(unsigned, r); }
; template <bool A_F32>
; DI void mini_gemm(f32x4 (&acc)[2][2], const void* Ap, int lda, const bf16_t* Bp, int ldb, int K, int wave, int l15, int quad) {
;   const int kw = K >> 2, k0 = wave * kw;
; #pragma unroll 2
;   for (int ks = 0; ks < kw; ks += 32) {
;     bf16x8 a[2], b[2];
; #pragma unroll
;     for (int mi = 0; mi < 2; ++mi) {
;       if (A_F32) {
;         const float* ap = (const float*)Ap + (size_t)(mi * 16 + l15) * lda + k0 + ks + quad * 8;
;         const f32x4 v0 = *(const f32x4*)ap, v1 = *(const f32x4*)(ap + 4);
;         u32x4 t; t[0] = pk2(v0[0], v0[1]); t[1] = pk2(v0[2], v0[3]); t[2] = pk2(v1[0], v1[1]); t[3] = pk2(v1[2], v1[3]);
;         a[mi] = __builtin_bit_cast(bf16x8, t);
;       } else {
;         a[mi] = *(const bf16x8*)((const bf16_t*)Ap + (size_t)(mi * 16 + l15) * lda + k0 + ks + quad * 8);
;       }
;       b[mi] = *(const bf16x8*)(Bp + (size_t)(mi * 16 + l15) * ldb + k0 + ks + quad * 8);
;     }
; #pragma unroll
;     for (int mi = 0; mi < 2; ++mi)
; #pragma unroll
;       for (int ni = 0; ni < 2; ++ni) acc[mi][ni] = __builtin_amdgcn_mfma_f32_16x16x32_bf16(b[ni], a[mi], acc[mi][ni], 0, 0, 0);
;   }
; }
; DI f32x4 mini_reduce(const f32x4 (&acc)[2][2], char* lds, int wave, int lane) {
;   float* red = (float*)lds;
;   __syncthreads();
; #pragma unroll
;   for (int i = 0; i < 2; ++i)
; #pragma unroll
;     for (int j = 0; j < 2; ++j)
; #pragma unroll
;       for (int e = 0; e < 4; ++e) red[((wave * 4 + i * 2 + j) * 4 + e) * 64 + lane] = acc[i][j][e];
;   __syncthreads();
;   f32x4 r;
; #pragma unroll
;   for (int e = 0; e < 4; ++e) r[e] = (red[((0 * 4 + wave) * 4 + e) * 64 + lane] + red[((1 * 4 + wave) * 4 + e) * 64 + lane]) + (red[((2 * 4 + wave) * 4 + e) * 64 + lane] + red[((3 * 4 + wave) * 4 + e) * 64 + lane]);
; DI void mini_ple(const Params& p, int l, int t, char* lds) {
;     ...
;   const f32x4 g = mini_reduce(acc, lds, wave, lane);
;   zero_mini(acc);
;   mini_gemm<true>(acc, p.ps + ((size_t)l * MS + (R0 - MP)) * 256, 256, p.wt_ple + (size_t)C0 * 256, 256, 256, wave, l15, quad);
;   const f32x4 e = mini_reduce(acc, lds, wave, lane);
	ds_read2st64_b32 v[4:5], v45 offset1:1
	ds_read2st64_b32 v[6:7], v45 offset0:16 offset1:17
	ds_read2st64_b32 v[8:9], v45 offset0:32 offset1:33
	ds_read2st64_b32 v[10:11], v45 offset0:48 offset1:49
	s_and_b32 s0, s0, -16
	s_add_i32 s1, s24, s0
	s_lshl_b32 s0, s31, 5
	s_ashr_i32 s25, s24, 31
	s_and_b32 s0, s0, 0x3e0
	s_lshl_b64 s[24:25], s[24:25], 10
	s_add_u32 s38, s20, s24
	v_readlane_b32 s68, v251, 49
	s_waitcnt lgkmcnt(3)
	v_mov_b32_e32 v2, v4
	s_waitcnt lgkmcnt(1)
	v_mov_b32_e32 v3, v8
	v_mov_b32_e32 v12, v6
	s_waitcnt lgkmcnt(0)
	v_mov_b32_e32 v13, v10
	v_mov_b32_e32 v8, v5
	v_mov_b32_e32 v10, v7
	s_addc_u32 s39, s21, s25
	s_lshl_b32 s24, s0, 9
	v_readlane_b32 s80, v251, 61
	v_pk_add_f32 v[2:3], v[2:3], v[12:13]
	v_pk_add_f32 v[4:5], v[8:9], v[10:11]
	ds_read2st64_b32 v[6:7], v45 offset0:2 offset1:3
	ds_read2st64_b32 v[8:9], v45 offset0:18 offset1:19
	ds_read2st64_b32 v[10:11], v45 offset0:34 offset1:35
	ds_read2st64_b32 v[12:13], v45 offset0:50 offset1:51
	v_readlane_b32 s81, v251, 62
	s_add_u32 s40, s80, s24
	s_addc_u32 s41, s81, 0
	s_and_b32 s24, s37, 0xffffffc0
	s_ashr_i32 s25, s24, 31
	s_lshl_b64 s[26:27], s[24:25], 2
	v_bfe_u32 v21, v19, 4, 2
	s_add_u32 s26, s38, s26
	v_and_b32_e32 v22, 15, v19
	v_add_f32_e32 v3, v2, v3
	v_add_f32_e32 v2, v4, v5
	s_waitcnt lgkmcnt(3)
	v_mov_b32_e32 v4, v6
	s_waitcnt lgkmcnt(1)
	v_mov_b32_e32 v5, v10
	v_mov_b32_e32 v14, v8
	s_waitcnt lgkmcnt(0)
	v_mov_b32_e32 v15, v12
	s_addc_u32 s27, s39, s27
	v_lshlrev_b32_e32 v0, 5, v21
	v_pk_add_f32 v[4:5], v[4:5], v[14:15]
	v_mov_b32_e32 v10, v7
	v_mov_b32_e32 v12, v9
	v_lshl_add_u64 v[14:15], s[26:27], 0, v[0:1]
	v_lshlrev_b32_e32 v0, 10, v22
	v_pk_add_f32 v[6:7], v[10:11], v[12:13]
	v_lshl_add_u64 v[32:33], v[14:15], 0, v[0:1]
	v_add_f32_e32 v5, v4, v5
	v_add_f32_e32 v4, v6, v7
	global_load_dwordx4 v[6:9], v[32:33], off offset:16
	global_load_dwordx4 v[10:13], v[32:33], off
	s_lshl_b64 s[24:25], s[24:25], 1
	s_add_u32 s24, s40, s24
	s_addc_u32 s25, s41, s25
	v_mov_b32_e32 v19, v1
	v_or_b32_e32 v23, 16, v22
	v_lshl_add_u64 v[18:19], s[24:25], 0, v[18:19]
	v_lshlrev_b32_e32 v0, 9, v22
	v_lshl_add_u64 v[36:37], v[18:19], 0, v[0:1]
	v_lshlrev_b32_e32 v0, 10, v23
	v_lshl_add_u64 v[40:41], v[14:15], 0, v[0:1]
	v_lshlrev_b32_e32 v0, 9, v23
	v_lshl_add_u64 v[18:19], v[18:19], 0, v[0:1]
	s_addk_i32 s1, 0x4000
	v_lshlrev_b32_e32 v0, 2, v21
	v_readlane_b32 s70, v251, 51
	v_readlane_b32 s71, v251, 52
	v_readlane_b32 s69, v251, 50
	v_readlane_b32 s72, v251, 53
	v_readlane_b32 s73, v251, 54
	v_readlane_b32 s74, v251, 55
	v_readlane_b32 s75, v251, 56
	v_readlane_b32 s76, v251, 57
	v_readlane_b32 s77, v251, 58
	v_readlane_b32 s78, v251, 59
	v_readlane_b32 s79, v251, 60
	v_readlane_b32 s82, v251, 63
	v_readlane_b32 s83, v252, 0
	s_waitcnt vmcnt(0)
	v_cvt_pk_bf16_f32 v10, v10, v11
	v_cvt_pk_bf16_f32 v11, v12, v13
	v_cvt_pk_bf16_f32 v12, v6, v7
	v_cvt_pk_bf16_f32 v13, v8, v9
	global_load_dwordx4 v[6:9], v[36:37], off
	global_load_dwordx4 v[14:17], v[40:41], off offset:16
	global_load_dwordx4 v[24:27], v[40:41], off
	s_waitcnt vmcnt(2)
	v_mfma_f32_16x16x32_bf16 v[28:31], v[6:9], v[10:13], 0
	s_waitcnt vmcnt(0)
	v_cvt_pk_bf16_f32 v24, v24, v25
	v_cvt_pk_bf16_f32 v25, v26, v27
	v_cvt_pk_bf16_f32 v26, v14, v15
	v_cvt_pk_bf16_f32 v27, v16, v17
	global_load_dwordx4 v[14:17], v[18:19], off
	s_waitcnt vmcnt(0)
	v_mfma_f32_16x16x32_bf16 v[10:13], v[14:17], v[10:13], 0
	v_mfma_f32_16x16x32_bf16 v[6:9], v[6:9], v[24:27], 0
	v_mfma_f32_16x16x32_bf16 v[14:17], v[14:17], v[24:27], 0
	global_load_dwordx4 v[24:27], v[32:33], off offset:144
	s_nop 0
	global_load_dwordx4 v[32:35], v[32:33], off offset:128
	s_waitcnt vmcnt(0)
	v_cvt_pk_bf16_f32 v32, v32, v33
	v_cvt_pk_bf16_f32 v33, v34, v35
	v_cvt_pk_bf16_f32 v34, v24, v25
	v_cvt_pk_bf16_f32 v35, v26, v27
	global_load_dwordx4 v[24:27], v[36:37], off offset:64
	s_nop 0
	global_load_dwordx4 v[36:39], v[40:41], off offset:144
	s_nop 0
	global_load_dwordx4 v[40:43], v[40:41], off offset:128
	s_waitcnt vmcnt(2)
	v_mfma_f32_16x16x32_bf16 v[28:31], v[24:27], v[32:35], v[28:31]
	s_waitcnt vmcnt(0)
	v_cvt_pk_bf16_f32 v40, v40, v41
	v_cvt_pk_bf16_f32 v41, v42, v43
	v_cvt_pk_bf16_f32 v42, v36, v37
	v_cvt_pk_bf16_f32 v43, v38, v39
	global_load_dwordx4 v[36:39], v[18:19], off offset:64
	s_nop 0
	v_mfma_f32_16x16x32_bf16 v[6:9], v[24:27], v[40:43], v[6:9]
	s_barrier
; DI unsigned pk2(float a, float b) { f32x2 v = {a, b}; bfv2 r = __builtin_convertvector(v, bfv2); return __builtin_bit_cast(unsigned, r); }
; DI float bf1(bf16_t u) { return __uint_as_float(((unsigned)u) << 16); }
; DI float sigmoidf_(float x) { return __builtin_amdgcn_rcpf(1.0f + __expf(-x)); }
; DI void mini_ple(const Params& p, int l, int t, char* lds) {
;     ...
;   const f32x4 e = mini_reduce(acc, lds, wave, lane);
;   const int R = R0 + (wave >> 1) * 16 + l15, c = C0 + (wave & 1) * 16 + quad * 4;
;   const float rs = rsqrtf(p.ss2[R] * (1.0f / 1024.0f) + 1e-6f);
;   float* xo = p.out + (size_t)R * DM + c;
;   const f32x4 xv = *(const f32x4*)xo;
;   f32x4 o;
; #pragma unroll
;   for (int k = 0; k < 4; ++k) o[k] = xv[k] + e[k] * bf1((bf16_t)(pk2(sigmoidf_(g[k] * rs), 0.f) & 0xffff));
;   *(f32x4*)xo = o;
;   if (l + 1 < NL) {
;     const f32x4 gn = *(const f32x4*)(p.norm_g + (l + 1) * DM + c);
;     u32x2 hv; hv[0] = pk2(o[0] * gn[0], o[1] * gn[1]); hv[1] = pk2(o[2] * gn[2], o[3] * gn[3]);
;     *(u32x2*)(p.hn + (size_t)R * DM + c) = hv;
;     float sq = o[0] * o[0] + o[1] * o[1] + o[2] * o[2] + o[3] * o[3];
;     sq += __shfl_xor(sq, 16); sq += __shfl_xor(sq, 32);
;     if (quad == 0) atomicAdd(p.ss1 + R, sq);
;   }
	s_waitcnt vmcnt(0)
	v_mfma_f32_16x16x32_bf16 v[10:13], v[36:39], v[32:35], v[10:13]
	v_mfma_f32_16x16x32_bf16 v[14:17], v[36:39], v[40:43], v[14:17]
	ds_write2st64_b32 v44, v28, v29 offset1:1
	ds_write2st64_b32 v44, v30, v31 offset0:2 offset1:3
	s_nop 4
	ds_write2st64_b32 v44, v10, v11 offset0:4 offset1:5
	ds_write2st64_b32 v44, v12, v13 offset0:6 offset1:7
	ds_write2st64_b32 v44, v6, v7 offset0:8 offset1:9
	ds_write2st64_b32 v44, v8, v9 offset0:10 offset1:11
	ds_write2st64_b32 v44, v14, v15 offset0:12 offset1:13
	ds_write2st64_b32 v44, v16, v17 offset0:14 offset1:15
	v_or_b32_e32 v6, s1, v22
	s_lshl_b32 s1, s36, 4
	v_readlane_b32 s36, v254, 52
	v_ashrrev_i32_e32 v7, 31, v6
	v_readlane_b32 s38, v254, 54
	v_readlane_b32 s39, v254, 55
	v_and_or_b32 v0, s1, 16, v0
	s_waitcnt lgkmcnt(0)
	v_lshl_add_u64 v[10:11], v[6:7], 2, s[38:39]
	s_barrier
	ds_read2st64_b32 v[14:15], v45 offset1:1
	ds_read2st64_b32 v[16:17], v45 offset0:16 offset1:17
	ds_read2st64_b32 v[18:19], v45 offset0:32 offset1:33
	ds_read2st64_b32 v[24:25], v45 offset0:48 offset1:49
	ds_read2st64_b32 v[26:27], v45 offset0:2 offset1:3
	ds_read2st64_b32 v[28:29], v45 offset0:18 offset1:19
	ds_read2st64_b32 v[30:31], v45 offset0:34 offset1:35
	ds_read2st64_b32 v[32:33], v45 offset0:50 offset1:51
	v_or_b32_e32 v8, s0, v0
	global_load_dword v0, v[10:11], off
	v_lshlrev_b64 v[10:11], 12, v[6:7]
	v_lshl_add_u64 v[10:11], s[70:71], 0, v[10:11]
	v_readlane_b32 s37, v254, 53
	v_readlane_b32 s40, v254, 56
	v_readlane_b32 s41, v254, 57
	v_readlane_b32 s42, v254, 58
	v_readlane_b32 s43, v254, 59
	s_waitcnt vmcnt(0)
	v_fmamk_f32 v0, v0, 0x3a800000, v249
	v_cmp_gt_f32_e32 vcc, s34, v0
	v_mul_f32_e32 v9, 0x4b800000, v0
	s_nop 0
	v_cndmask_b32_e32 v0, v0, v9, vcc
	v_rsq_f32_e32 v0, v0
	s_nop 0
	v_mul_f32_e32 v9, 0x45800000, v0
	v_cndmask_b32_e32 v9, v0, v9, vcc
	v_lshlrev_b32_e32 v0, 2, v8
	v_lshl_add_u64 v[22:23], v[10:11], 0, v[0:1]
	global_load_dwordx4 v[10:13], v[22:23], off
	v_mul_f32_e32 v3, v3, v9
	v_mul_f32_e32 v2, v2, v9
	v_mul_f32_e32 v3, 0xbfb8aa3b, v3
	v_mul_f32_e32 v2, 0xbfb8aa3b, v2
	v_exp_f32_e32 v3, v3
	v_exp_f32_e32 v2, v2
	v_mul_f32_e32 v5, v5, v9
	v_mul_f32_e32 v4, v4, v9
	v_add_f32_e32 v3, 1.0, v3
	v_add_f32_e32 v2, 1.0, v2
	v_rcp_f32_e32 v21, v3
	v_rcp_f32_e32 v34, v2
	v_mul_f32_e32 v5, 0xbfb8aa3b, v5
	v_mul_f32_e32 v4, 0xbfb8aa3b, v4
	v_exp_f32_e32 v5, v5
	v_exp_f32_e32 v4, v4
	s_waitcnt lgkmcnt(6)
	v_pk_add_f32 v[2:3], v[14:15], v[16:17]
	s_waitcnt lgkmcnt(4)
	v_pk_add_f32 v[14:15], v[18:19], v[24:25]
	v_add_f32_e32 v5, 1.0, v5
	v_pk_add_f32 v[2:3], v[2:3], v[14:15]
	v_cvt_pk_bf16_f32 v14, v21, v34
	v_and_b32_e32 v15, 0xffff0000, v14
	v_lshlrev_b32_e32 v14, 16, v14
	v_add_f32_e32 v4, 1.0, v4
	v_rcp_f32_e32 v9, v4
	s_andn2_b64 vcc, exec, s[2:3]
	s_waitcnt vmcnt(0)
	v_pk_fma_f32 v[2:3], v[2:3], v[14:15], v[10:11]
	v_rcp_f32_e32 v14, v5
	s_waitcnt lgkmcnt(2)
	v_pk_add_f32 v[4:5], v[26:27], v[28:29]
	s_waitcnt lgkmcnt(0)
	v_pk_add_f32 v[10:11], v[30:31], v[32:33]
	v_cvt_pk_bf16_f32 v9, v14, v9
	v_pk_add_f32 v[4:5], v[4:5], v[10:11]
	v_and_b32_e32 v11, 0xffff0000, v9
	v_lshlrev_b32_e32 v10, 16, v9
	v_pk_fma_f32 v[4:5], v[4:5], v[10:11], v[12:13]
	global_store_dwordx4 v[22:23], v[2:5], off
	s_cbranch_vccnz .LBB0_954
	global_load_dwordx4 v[10:13], v0, s[22:23]
	v_lshlrev_b64 v[14:15], 10, v[6:7]
	v_lshlrev_b32_e32 v0, 1, v8
	s_waitcnt vmcnt(0)
	v_pk_mul_f32 v[10:11], v[2:3], v[10:11]
	v_pk_mul_f32 v[12:13], v[4:5], v[12:13]
	v_cvt_pk_bf16_f32 v10, v10, v11
	v_cvt_pk_bf16_f32 v11, v12, v13
	v_lshl_add_u64 v[12:13], v[14:15], 1, s[8:9]
	v_pk_mul_f32 v[2:3], v[2:3], v[2:3]
	v_lshl_add_u64 v[8:9], v[12:13], 0, v[0:1]
	v_add_f32_e32 v0, v2, v3
	v_add_u32_e32 v2, 64, v137
	v_pk_mul_f32 v[4:5], v[4:5], v[4:5]
	v_cmp_lt_i32_e32 vcc, v136, v2
	v_add_f32_e32 v0, v4, v0
	v_add_f32_e32 v0, v5, v0
	v_cndmask_b32_e32 v3, v218, v136, vcc
	v_lshlrev_b32_e32 v3, 2, v3
	ds_bpermute_b32 v3, v3, v0
	v_cmp_lt_i32_e32 vcc, v138, v2
	global_store_dwordx2 v[8:9], v[10:11], off
	s_waitcnt lgkmcnt(0)
	v_add_f32_e32 v0, v0, v3
	v_cndmask_b32_e32 v2, v218, v138, vcc
	v_lshlrev_b32_e32 v2, 2, v2
	ds_bpermute_b32 v2, v2, v0
	v_cmp_gt_u32_e32 vcc, 16, v20
	s_and_saveexec_b64 s[0:1], vcc
	s_cbranch_execz .LBB0_953
	v_readlane_b32 s36, v254, 52
	v_readlane_b32 s37, v254, 53
	s_waitcnt lgkmcnt(0)
	v_add_f32_e32 v0, v0, v2
	v_readlane_b32 s38, v254, 54
	v_lshl_add_u64 v[4:5], v[6:7], 2, s[36:37]
	global_atomic_add_f32 v[4:5], v0, off
	v_readlane_b32 s39, v254, 55
	v_readlane_b32 s40, v254, 56
	v_readlane_b32 s41, v254, 57
	v_readlane_b32 s42, v254, 58
	v_readlane_b32 s43, v254, 59
	s_branch .LBB0_953
